# attention: one staging barrier per half-tile (V tiles rotate over 4 LDS buffers; all staging writes issued right after P.V)
# baseline (speedup 1.0000x reference)
; #define SLOADA(k0) do { vsA0 = *(const bf16x8*)(&Vh[(size_t)((k0) + sr) * LDP + sc]); vsA1 = *(const bf16x8*)(&Vh[(size_t)((k0) + 32 + sr) * LDP + sc]); \
;     ksA0 = *(const bf16x8*)(&Kh[(size_t)((k0) + sr) * LDP + sc]); ksA1 = *(const bf16x8*)(&Kh[(size_t)((k0) + 32 + sr) * LDP + sc]); } while (0)
; #define SLOADB(k0) do { vsB0 = *(const bf16x8*)(&Vh[(size_t)((k0) + sr) * LDP + sc]); vsB1 = *(const bf16x8*)(&Vh[(size_t)((k0) + 32 + sr) * LDP + sc]); \
;     ksB0 = *(const bf16x8*)(&Kh[(size_t)((k0) + sr) * LDP + sc]); ksB1 = *(const bf16x8*)(&Kh[(size_t)((k0) + 32 + sr) * LDP + sc]); } while (0)
; #define SWRITEA(b) do { *(bf16x8*)(V_lds + (b) * SHM_V + vst0) = vsA0; *(bf16x8*)(V_lds + (b) * SHM_V + vst1) = vsA1; const int kc = sc * 2; \
;     *(bf16x8*)(K_lds + (b) * SHM_K + KSWZ(sr, kc)) = ksA0; *(bf16x8*)(K_lds + (b) * SHM_K + KSWZ(32 + sr, kc)) = ksA1; } while (0)
; #define SWRITEB(b) do { *(bf16x8*)(V_lds + (b) * SHM_V + vst0) = vsB0; *(bf16x8*)(V_lds + (b) * SHM_V + vst1) = vsB1; const int kc = sc * 2; \
;     *(bf16x8*)(K_lds + (b) * SHM_K + KSWZ(sr, kc)) = ksB0; *(bf16x8*)(K_lds + (b) * SHM_K + KSWZ(32 + sr, kc)) = ksB1; } while (0)
; #define SWAIT() asm volatile("s_waitcnt vmcnt(4)" ::: "memory")
; __device__ __forceinline__ void attn_unit(const bf16* __restrict__ P, bf16* __restrict__ MIXIN, const float* __restrict__ gn, int seq0, int h, int q0, int nt, float kmax0, float kmax1, float slope, float lam, char* lds) {
;     ...
;   SLOADA(t0 * 64); asm volatile("s_waitcnt vmcnt(0)" ::: "memory"); SWRITEA(0); __syncthreads();
;   SLOADB((t0 + 1) * 64); if (t0 + 2 < t1) SLOADA((t0 + 2) * 64);
;   sc_init(pA0, pA1, DQ(t0), nsl2, m_reg, SIDE(t0)); qk_only(pA0, pA1, K_lds, qr, r32, hi, cbase);
; #pragma unroll
;   for (int r = 0; r < 16; ++r) { pA0[r] = __builtin_amdgcn_exp2f(pA0[r]); pA1[r] = __builtin_amdgcn_exp2f(pA1[r]); }
;   SWAIT(); SWRITEB(1); __syncthreads();
;   for (int j = t0 + 1; j + 1 < t1; j += 2) {
.LBB0_320:
	v_lshlrev_b32_e32 v34, 4, v36
	v_lshlrev_b32_e32 v232, 8, v36
	v_lshlrev_b32_e32 v32, 1, v32
	v_and_b32_e32 v34, 0x70, v34
	v_add_u32_e32 v35, 0, v232
	v_bitop3_b32 v236, v32, v34, v176 bitop3:0x36
	v_add_u32_e32 v241, v35, v236
	ds_read_b128 v[38:41], v241 offset:32768
	ds_read_b128 v[42:45], v241 offset:40960
	s_waitcnt lgkmcnt(1)
	v_mfma_f32_32x32x16_bf16 v[16:31], v[38:41], v[132:135], v[16:31]
	v_or_b32_e32 v32, v32, v176
	v_bitop3_b32 v235, v32, v34, 32 bitop3:0x36
	v_add_u32_e32 v242, v35, v235
	v_bitop3_b32 v234, v32, v34, 64 bitop3:0x36
	v_add_u32_e32 v243, v35, v234
	s_movk_i32 s6, 0x60
	v_bitop3_b32 v233, v32, v34, s6 bitop3:0x36
	s_waitcnt lgkmcnt(0)
	v_mfma_f32_32x32x16_bf16 v[0:15], v[42:45], v[132:135], v[0:15]
	ds_read_b128 v[38:41], v242 offset:32768
	ds_read_b128 v[42:45], v242 offset:40960
	v_lshlrev_b32_e32 v32, 4, v33
	v_add_u32_e32 v244, v35, v233
	v_lshlrev_b32_e32 v36, 3, v33
	v_and_b32_e32 v32, 0xc0, v32
	s_cmp_lg_u32 0, -1
	s_cselect_b32 s6, 0, 0
	s_waitcnt lgkmcnt(1)
	v_mfma_f32_32x32x16_bf16 v[16:31], v[38:41], v[128:131], v[16:31]
	s_andn2_b64 vcc, exec, s[0:1]
	s_waitcnt lgkmcnt(0)
	v_mfma_f32_32x32x16_bf16 v[0:15], v[42:45], v[128:131], v[0:15]
	ds_read_b128 v[38:41], v243 offset:32768
	ds_read_b128 v[42:45], v243 offset:40960
	s_waitcnt lgkmcnt(1)
	v_mfma_f32_32x32x16_bf16 v[16:31], v[38:41], v[140:143], v[16:31]
	ds_read_b128 v[38:41], v244 offset:32768
	s_waitcnt lgkmcnt(1)
	v_mfma_f32_32x32x16_bf16 v[0:15], v[42:45], v[140:143], v[0:15]
	v_and_or_b32 v42, v36, 24, v32
	v_lshlrev_b32_e32 v43, 1, v33
	ds_read_b128 v[32:35], v244 offset:40960
	v_and_b32_e32 v36, 0x100, v36
	s_waitcnt vmcnt(4)
	s_waitcnt vmcnt(3)
	ds_write_b128 v239, v[160:163] offset:16384
	s_waitcnt vmcnt(1)
	ds_write_b128 v240, v[168:171] offset:16384
	ds_write_b128 v237, v[164:167] offset:49152
	s_waitcnt vmcnt(0)
	ds_write_b128 v238, v[172:175] offset:49152
	s_waitcnt lgkmcnt(0)
	v_mfma_f32_32x32x16_bf16 v[16:31], v[38:41], v[136:139], v[16:31]
	v_and_b32_e32 v38, 32, v43
	v_or3_b32 v176, v42, v38, v36
	v_add_u32_e32 v230, s6, v176
	s_barrier
	s_nop 7
	v_exp_f32_e32 v80, v16
	v_mfma_f32_32x32x16_bf16 v[0:15], v[32:35], v[136:139], v[0:15]
	v_exp_f32_e32 v81, v17
	v_exp_f32_e32 v82, v18
	v_exp_f32_e32 v83, v19
	v_exp_f32_e32 v84, v20
	v_exp_f32_e32 v85, v21
	v_exp_f32_e32 v86, v22
	v_exp_f32_e32 v87, v23
	s_nop 4
	v_exp_f32_e32 v64, v0
	v_exp_f32_e32 v65, v1
	v_exp_f32_e32 v66, v2
	v_exp_f32_e32 v67, v3
	v_exp_f32_e32 v68, v4
	v_exp_f32_e32 v69, v5
	v_exp_f32_e32 v70, v6
	v_exp_f32_e32 v71, v7
	v_exp_f32_e32 v88, v24
	v_exp_f32_e32 v72, v8
	v_exp_f32_e32 v89, v25
	v_exp_f32_e32 v73, v9
	v_exp_f32_e32 v90, v26
	v_exp_f32_e32 v74, v10
	v_exp_f32_e32 v91, v27
	v_exp_f32_e32 v75, v11
	v_exp_f32_e32 v92, v28
	v_exp_f32_e32 v76, v12
	v_exp_f32_e32 v93, v29
	v_exp_f32_e32 v77, v13
	v_exp_f32_e32 v94, v30
	v_exp_f32_e32 v78, v14
	v_exp_f32_e32 v95, v31
	v_exp_f32_e32 v79, v15
	v_mov_b32_e32 v15, 0
	s_mov_b32 s100, 0
	s_cbranch_vccnz .LBB0_335
	s_cmp_lg_u32 0, -1
	s_cselect_b32 s0, 0, 0
	v_xor_b32_e32 v186, 0x80000000, v182
	s_addk_i32 s0, 0x4000
	v_mov_b32_e32 v231, 0
	v_mov_b32_e32 v222, v214
	v_add_u32_e32 v245, s0, v176
	v_mov_b32_e32 v188, v180
	v_mov_b32_e32 v189, v180
	v_mov_b32_e32 v187, v186
	v_mov_b32_e32 v190, v180
	v_mov_b32_e32 v191, v180
	v_mov_b32_e32 v192, v186
	v_mov_b32_e32 v193, v186
	v_mov_b32_e32 v194, v186
	v_mov_b32_e32 v195, v186
	v_mov_b32_e32 v196, v186
	v_mov_b32_e32 v197, v186
	v_mov_b32_e32 v198, v186
	v_mov_b32_e32 v199, v186
	v_mov_b32_e32 v200, v186
	v_mov_b32_e32 v201, v186
	v_mov_b32_e32 v202, v186
	v_mov_b32_e32 v203, v186
	v_mov_b32_e32 v204, v186
	v_mov_b32_e32 v205, v186
	v_mov_b32_e32 v206, v186
	v_mov_b32_e32 v207, v186
	v_add_u32_e32 v246, 0x120, v37
	v_mov_b32_e32 v48, 0
	v_mov_b32_e32 v49, v231
	v_mov_b32_e32 v50, v231
	v_mov_b32_e32 v51, v231
	v_mov_b32_e32 v52, v231
	v_mov_b32_e32 v53, v231
	v_mov_b32_e32 v54, v231
	v_mov_b32_e32 v55, v231
	v_mov_b32_e32 v56, v231
	v_mov_b32_e32 v57, v231
	v_mov_b32_e32 v58, v231
	v_mov_b32_e32 v59, v231
	v_mov_b32_e32 v60, v231
	v_mov_b32_e32 v61, v231
	v_mov_b32_e32 v62, v231
	v_mov_b32_e32 v63, v231
	v_mov_b32_e32 v32, 0
	v_mov_b32_e32 v33, v231
	v_mov_b32_e32 v34, v231
	v_mov_b32_e32 v35, v231
	v_mov_b32_e32 v36, v231
	v_mov_b32_e32 v37, v231
	v_mov_b32_e32 v38, v231
	v_mov_b32_e32 v39, v231
	v_mov_b32_e32 v40, v231
	v_mov_b32_e32 v41, v231
	v_mov_b32_e32 v42, v231
	v_mov_b32_e32 v43, v231
	v_mov_b32_e32 v44, v231
	v_mov_b32_e32 v45, v231
	v_mov_b32_e32 v46, v231
	v_mov_b32_e32 v47, v231
	v_mov_b32_e32 v16, 0
	v_mov_b32_e32 v17, v231
	v_mov_b32_e32 v18, v231
	v_mov_b32_e32 v19, v231
	v_mov_b32_e32 v20, v231
	v_mov_b32_e32 v21, v231
	v_mov_b32_e32 v22, v231
	v_mov_b32_e32 v23, v231
	v_mov_b32_e32 v24, v231
	v_mov_b32_e32 v25, v231
	v_mov_b32_e32 v26, v231
	v_mov_b32_e32 v27, v231
	v_mov_b32_e32 v28, v231
	v_mov_b32_e32 v29, v231
	v_mov_b32_e32 v30, v231
	v_mov_b32_e32 v31, v231
	v_mov_b32_e32 v0, 0
	v_mov_b32_e32 v1, v231
	v_mov_b32_e32 v2, v231
	v_mov_b32_e32 v3, v231
	v_mov_b32_e32 v4, v231
	v_mov_b32_e32 v5, v231
	v_mov_b32_e32 v6, v231
	v_mov_b32_e32 v7, v231
	v_mov_b32_e32 v8, v231
	v_mov_b32_e32 v9, v231
	v_mov_b32_e32 v10, v231
	v_mov_b32_e32 v11, v231
	v_mov_b32_e32 v12, v231
	v_mov_b32_e32 v13, v231
	v_mov_b32_e32 v14, v231
	v_mov_b32_e32 v15, v231
	v_xor_b32_e32 v239, 0x18000, v239
	v_xor_b32_e32 v240, 0x18000, v240
	s_add_i32 s0, s33, 1
	s_cmp_ge_i32 s0, s3
	s_cbranch_scc1 .LBB0_323

; #define SBAR() __builtin_amdgcn_sched_barrier(0)
; #define SLOADA(k0) do { vsA0 = *(const bf16x8*)(&Vh[(size_t)((k0) + sr) * LDP + sc]); vsA1 = *(const bf16x8*)(&Vh[(size_t)((k0) + 32 + sr) * LDP + sc]); \
;     ksA0 = *(const bf16x8*)(&Kh[(size_t)((k0) + sr) * LDP + sc]); ksA1 = *(const bf16x8*)(&Kh[(size_t)((k0) + 32 + sr) * LDP + sc]); } while (0)
; #define SWRITEA(b) do { *(bf16x8*)(V_lds + (b) * SHM_V + vst0) = vsA0; *(bf16x8*)(V_lds + (b) * SHM_V + vst1) = vsA1; const int kc = sc * 2; \
;     *(bf16x8*)(K_lds + (b) * SHM_K + KSWZ(sr, kc)) = ksA0; *(bf16x8*)(K_lds + (b) * SHM_K + KSWZ(32 + sr, kc)) = ksA1; } while (0)
; #define SWAIT() asm volatile("s_waitcnt vmcnt(4)" ::: "memory")
; __device__ __forceinline__ void attn_unit(const bf16* __restrict__ P, bf16* __restrict__ MIXIN, const float* __restrict__ gn, int seq0, int h, int q0, int nt, float kmax0, float kmax1, float slope, float lam, char* lds) {
;     ...
;     __syncthreads(); SWAIT(); SWRITEA(0); __syncthreads();
;     if (j + 3 < t1) SLOADA((j + 3) * 64); SBAR();
.Lattn_nocalcA:
	s_waitcnt vmcnt(4)
	ds_write_b128 v237, v[148:151] offset:32768
	ds_write_b128 v238, v[156:159] offset:32768
	ds_write_b128 v239, v[144:147]
	ds_write_b128 v240, v[152:155]
	s_cmp_ge_i32 s76, s3
	s_cselect_b64 s[0:1], -1, 0
	s_and_b64 vcc, exec, s[0:1]
	s_waitcnt lgkmcnt(0)
	s_barrier
	s_cbranch_vccnz .LBB0_328
	global_load_dwordx4 v[144:147], v[214:215], off offset:2048
	global_load_dwordx4 v[148:151], v[214:215], off offset:1024
	global_load_dwordx4 v[152:155], v[216:217], off offset:2048
	global_load_dwordx4 v[156:159], v[216:217], off offset:1024

; #define SWRITEB(b) do { *(bf16x8*)(V_lds + (b) * SHM_V + vst0) = vsB0; *(bf16x8*)(V_lds + (b) * SHM_V + vst1) = vsB1; const int kc = sc * 2; \
;     *(bf16x8*)(K_lds + (b) * SHM_K + KSWZ(sr, kc)) = ksB0; *(bf16x8*)(K_lds + (b) * SHM_K + KSWZ(32 + sr, kc)) = ksB1; } while (0)
; #define SWAIT() asm volatile("s_waitcnt vmcnt(4)" ::: "memory")
; __device__ __forceinline__ void attn_unit(const bf16* __restrict__ P, bf16* __restrict__ MIXIN, const float* __restrict__ gn, int seq0, int h, int q0, int nt, float kmax0, float kmax1, float slope, float lam, char* lds) {
;     ...
;     __syncthreads(); SWAIT(); SWRITEB(1); __syncthreads();
;   }
.Lattn_kwB:
	ds_write_b128 v237, v[164:167] offset:49152
	ds_write_b128 v238, v[172:175] offset:49152
	ds_write_b128 v239, v[160:163] offset:16384
	ds_write_b128 v240, v[168:171] offset:16384
	v_xor_b32_e32 v230, 0x18000, v230
	v_xor_b32_e32 v245, 0x18000, v245
	v_xor_b32_e32 v239, 0x18000, v239
	v_xor_b32_e32 v240, 0x18000, v240
	s_xor_b32 s100, s100, 0x18000
	s_and_b64 vcc, exec, s[0:1]
	s_waitcnt vmcnt(0)
	s_waitcnt lgkmcnt(0)
	s_barrier
	s_cbranch_vccnz .LBB0_336
	s_mov_b32 s33, s76
	s_add_i32 s0, s33, 1
	s_cmp_ge_i32 s0, s3
	s_cbranch_scc1 .LBB0_326
	global_load_dwordx4 v[160:163], v[214:215], off offset:2048
	global_load_dwordx4 v[164:167], v[214:215], off offset:1024
	global_load_dwordx4 v[168:171], v[216:217], off offset:2048
	global_load_dwordx4 v[172:175], v[216:217], off offset:1024
	s_branch .LBB0_326

; #define SBAR() __builtin_amdgcn_sched_barrier(0)
; __device__ __forceinline__ void attn_unit(const bf16* __restrict__ P, bf16* __restrict__ MIXIN, const float* __restrict__ gn, int seq0, int h, int q0, int nt, float kmax0, float kmax1, float slope, float lam, char* lds) {
;     ...
;   sc_init(pB0, pB1, DQ(t1 - 1), nsl2, m_reg, SIDE(t1 - 1)); SBAR();
;   qk_fin(pB0, pB1, K_lds + SHM_K, qr, r32, hi, cbase, pA0, pA1, l_reg, pa0, pa1, pa2, pa3);
;   pv_exp(o, vb0, pa0, pa1, pa2, pa3, pB0, pB1);
.LBB0_340:
	v_and_b32_e32 v144, 0x3fffffc0, v229
	v_lshl_add_u32 v144, v144, 2, s10
	v_add3_u32 v145, 0, v236, v232
	ds_read_b128 v[146:149], v145 offset:49152
	ds_read_b128 v[150:153], v145 offset:57344
	s_waitcnt lgkmcnt(1)
	v_mfma_f32_32x32x16_bf16 v[112:127], v[146:149], v[132:135], v[112:127]
	s_waitcnt lgkmcnt(0)
	v_mfma_f32_32x32x16_bf16 v[96:111], v[150:153], v[132:135], v[96:111]
	v_add_f32_e32 v132, 0, v80
	v_add_f32_e32 v132, v81, v132
	v_add_f32_e32 v132, v82, v132
	v_add_f32_e32 v132, v83, v132
	v_add_f32_e32 v132, v84, v132
	v_add_f32_e32 v132, v85, v132
	v_add_f32_e32 v132, v86, v132
	v_cvt_pk_bf16_f32 v80, v80, v81
	v_cvt_pk_bf16_f32 v81, v82, v83
	v_cvt_pk_bf16_f32 v82, v84, v85
	v_cvt_pk_bf16_f32 v83, v86, v87
	v_add_f32_e32 v132, v87, v132
	v_permlane32_swap_b32_e32 v80, v82
	v_permlane32_swap_b32_e32 v81, v83
	v_add3_u32 v133, 0, v235, v232
	ds_read_b128 v[84:87], v133 offset:49152
	v_add_f32_e32 v145, v88, v132
	ds_read_b128 v[132:135], v133 offset:57344
	v_add_f32_e32 v145, v89, v145
	v_add_f32_e32 v145, v90, v145
	s_waitcnt lgkmcnt(1)
	v_mfma_f32_32x32x16_bf16 v[112:127], v[84:87], v[128:131], v[112:127]
	v_add_f32_e32 v84, v91, v145
	v_add_f32_e32 v84, v92, v84
	v_add_f32_e32 v84, v93, v84
	v_add_f32_e32 v84, v94, v84
	v_add_f32_e32 v145, v95, v84
	v_cvt_pk_bf16_f32 v84, v88, v89
	v_cvt_pk_bf16_f32 v85, v90, v91
	v_cvt_pk_bf16_f32 v86, v92, v93
	v_cvt_pk_bf16_f32 v87, v94, v95
	s_waitcnt lgkmcnt(0)
	v_mfma_f32_32x32x16_bf16 v[96:111], v[132:135], v[128:131], v[96:111]
	v_permlane32_swap_b32_e32 v84, v86
	v_permlane32_swap_b32_e32 v85, v87
	v_add3_u32 v92, 0, v234, v232
	ds_read_b128 v[88:91], v92 offset:49152
	ds_read_b128 v[92:95], v92 offset:57344
	v_add_f32_e32 v128, v64, v145
	v_add_f32_e32 v128, v65, v128
	v_add_f32_e32 v128, v66, v128
	v_cvt_pk_bf16_f32 v64, v64, v65
	v_cvt_pk_bf16_f32 v65, v66, v67
	v_cvt_pk_bf16_f32 v66, v68, v69
	s_waitcnt lgkmcnt(1)
	v_mfma_f32_32x32x16_bf16 v[112:127], v[88:91], v[140:143], v[112:127]
	v_add_f32_e32 v88, v67, v128
	v_add_f32_e32 v88, v68, v88
	v_add_f32_e32 v88, v69, v88
	v_add_f32_e32 v88, v70, v88
	v_cvt_pk_bf16_f32 v67, v70, v71
	v_add_f32_e32 v128, v71, v88
	v_permlane32_swap_b32_e32 v64, v66
	v_permlane32_swap_b32_e32 v65, v67
	s_waitcnt lgkmcnt(0)
	v_mfma_f32_32x32x16_bf16 v[96:111], v[92:95], v[140:143], v[96:111]
	v_add3_u32 v88, 0, v233, v232
	ds_read_b128 v[68:71], v88 offset:49152
	ds_read_b128 v[88:91], v88 offset:57344
	s_waitcnt lgkmcnt(1)
	v_mfma_f32_32x32x16_bf16 v[112:127], v[68:71], v[136:139], v[112:127]
	v_add_f32_e32 v68, v72, v128
	v_add_f32_e32 v68, v73, v68
	v_add_f32_e32 v68, v74, v68
	v_add_f32_e32 v68, v75, v68
	v_add_f32_e32 v68, v76, v68
	v_add_f32_e32 v68, v77, v68
	v_add_f32_e32 v68, v78, v68
	s_waitcnt lgkmcnt(0)
	v_mfma_f32_32x32x16_bf16 v[96:111], v[88:91], v[136:139], v[96:111]
	v_add_f32_e32 v88, v79, v68
	v_cvt_pk_bf16_f32 v68, v72, v73
	v_cvt_pk_bf16_f32 v69, v74, v75
	v_cvt_pk_bf16_f32 v70, v76, v77
	v_mov_b32_e32 v72, v88
	v_cvt_pk_bf16_f32 v71, v78, v79
	v_permlane32_swap_b32_e32 v68, v70
	s_nop 0
	v_permlane32_swap_b32_e32 v88, v72
	v_permlane32_swap_b32_e32 v69, v71
	ds_read_b64_tr_b16 v[74:75], v230 offset:0
	ds_read_b64_tr_b16 v[76:77], v230 offset:0x800
	ds_read_b64_tr_b16 v[90:91], v230 offset:0x1000
	ds_read_b64_tr_b16 v[92:93], v230 offset:0x1800
	ds_read_b64_tr_b16 v[128:129], v230 offset:0x2000
	ds_read_b64_tr_b16 v[130:131], v230 offset:0x2800
	ds_read_b64_tr_b16 v[132:133], v230 offset:0x3000
	ds_read_b64_tr_b16 v[134:135], v230 offset:0x3800
	s_waitcnt lgkmcnt(0)
	s_nop 0
	v_mfma_f32_32x32x16_bf16 v[48:63], v[80:83], v[74:77], v[48:63]
	v_exp_f32_e32 v112, v112
	v_exp_f32_e32 v113, v113
	v_exp_f32_e32 v114, v114
	v_exp_f32_e32 v115, v115
	v_exp_f32_e32 v116, v116
	v_exp_f32_e32 v117, v117
	v_exp_f32_e32 v118, v118
	v_mfma_f32_32x32x16_bf16 v[48:63], v[84:87], v[90:93], v[48:63]
	v_exp_f32_e32 v119, v119
	v_mfma_f32_32x32x16_bf16 v[48:63], v[64:67], v[128:131], v[48:63]
	v_mfma_f32_32x32x16_bf16 v[48:63], v[68:71], v[132:135], v[48:63]
	ds_read_b64_tr_b16 v[74:75], v230 offset:0x200
	ds_read_b64_tr_b16 v[76:77], v230 offset:0xa00
	ds_read_b64_tr_b16 v[90:91], v230 offset:0x1200
	ds_read_b64_tr_b16 v[92:93], v230 offset:0x1a00
	ds_read_b64_tr_b16 v[128:129], v230 offset:0x2200
	ds_read_b64_tr_b16 v[130:131], v230 offset:0x2a00
	ds_read_b64_tr_b16 v[132:133], v230 offset:0x3200
	ds_read_b64_tr_b16 v[134:135], v230 offset:0x3a00
	s_waitcnt lgkmcnt(0)
	s_nop 0
	v_mfma_f32_32x32x16_bf16 v[32:47], v[80:83], v[74:77], v[32:47]
	v_exp_f32_e32 v120, v120
	v_exp_f32_e32 v121, v121
	v_exp_f32_e32 v122, v122
	v_exp_f32_e32 v123, v123
	v_exp_f32_e32 v124, v124
	v_exp_f32_e32 v125, v125
	v_exp_f32_e32 v126, v126
	v_mfma_f32_32x32x16_bf16 v[32:47], v[84:87], v[90:93], v[32:47]
	v_exp_f32_e32 v127, v127
	v_mfma_f32_32x32x16_bf16 v[32:47], v[64:67], v[128:131], v[32:47]
	v_mfma_f32_32x32x16_bf16 v[32:47], v[68:71], v[132:135], v[32:47]
	ds_read_b64_tr_b16 v[74:75], v230 offset:0x400
	ds_read_b64_tr_b16 v[76:77], v230 offset:0xc00
	ds_read_b64_tr_b16 v[90:91], v230 offset:0x1400
	ds_read_b64_tr_b16 v[92:93], v230 offset:0x1c00
	ds_read_b64_tr_b16 v[128:129], v230 offset:0x2400
	ds_read_b64_tr_b16 v[130:131], v230 offset:0x2c00
	ds_read_b64_tr_b16 v[132:133], v230 offset:0x3400
	ds_read_b64_tr_b16 v[134:135], v230 offset:0x3c00
	s_waitcnt lgkmcnt(0)
; __device__ __forceinline__ void fin_only(const f32x16& q0, const f32x16& q1, float& l_reg, bf16x8& pa0, bf16x8& pa1, bf16x8& pa2, bf16x8& pa3) {
;   float ps = 0.f;
; #pragma unroll
;   for (int r = 0; r < 16; ++r) ps += q0[r];
; #pragma unroll
;   for (int r = 0; r < 16; ++r) ps += q1[r];
;   { auto rr = __builtin_amdgcn_permlane32_swap(__float_as_uint(ps), __float_as_uint(ps), false, false); ps = __uint_as_float(rr[0]) + __uint_as_float(rr[1]); }
;   l_reg += ps; PK4(q0, 0, pa0); PK4(q0, 8, pa1); PK4(q1, 0, pa2); PK4(q1, 8, pa3);
; }
; __device__ __forceinline__ void pv_d0(f32x16* o, int vb, bf16x8 pa0, bf16x8 pa1, bf16x8 pa2, bf16x8 pa3) {
;   pv_one<0>(o[0], vb, pa0, pa1, pa2, pa3); pv_one<1>(o[1], vb, pa0, pa1, pa2, pa3); pv_one<2>(o[2], vb, pa0, pa1, pa2, pa3); pv_one<3>(o[3], vb, pa0, pa1, pa2, pa3);
; }
	s_nop 0
	v_mfma_f32_32x32x16_bf16 v[16:31], v[80:83], v[74:77], v[16:31]
	v_exp_f32_e32 v96, v96
	v_exp_f32_e32 v97, v97
	v_exp_f32_e32 v98, v98
	v_exp_f32_e32 v99, v99
	v_exp_f32_e32 v100, v100
	v_exp_f32_e32 v101, v101
	v_exp_f32_e32 v102, v102
	v_mfma_f32_32x32x16_bf16 v[16:31], v[84:87], v[90:93], v[16:31]
	v_exp_f32_e32 v103, v103
	v_mfma_f32_32x32x16_bf16 v[16:31], v[64:67], v[128:131], v[16:31]
	v_mfma_f32_32x32x16_bf16 v[16:31], v[68:71], v[132:135], v[16:31]
	ds_read_b64_tr_b16 v[74:75], v230 offset:0x600
	ds_read_b64_tr_b16 v[76:77], v230 offset:0xe00
	ds_read_b64_tr_b16 v[90:91], v230 offset:0x1600
	ds_read_b64_tr_b16 v[92:93], v230 offset:0x1e00
	ds_read_b64_tr_b16 v[128:129], v230 offset:0x2600
	ds_read_b64_tr_b16 v[130:131], v230 offset:0x2e00
	ds_read_b64_tr_b16 v[132:133], v230 offset:0x3600
	ds_read_b64_tr_b16 v[134:135], v230 offset:0x3e00
	s_waitcnt lgkmcnt(0)
	s_nop 0
	v_mfma_f32_32x32x16_bf16 v[0:15], v[80:83], v[74:77], v[0:15]
	v_exp_f32_e32 v104, v104
	v_exp_f32_e32 v105, v105
	v_exp_f32_e32 v106, v106
	v_exp_f32_e32 v107, v107
	v_exp_f32_e32 v108, v108
	v_exp_f32_e32 v109, v109
	v_exp_f32_e32 v110, v110
	v_mfma_f32_32x32x16_bf16 v[0:15], v[84:87], v[90:93], v[0:15]
	v_exp_f32_e32 v111, v111
	v_mfma_f32_32x32x16_bf16 v[0:15], v[64:67], v[128:131], v[0:15]
	v_mfma_f32_32x32x16_bf16 v[0:15], v[68:71], v[132:135], v[0:15]
	v_add_f32_e32 v64, 0, v112
	v_add_f32_e32 v64, v113, v64
	v_add_f32_e32 v64, v114, v64
	v_add_f32_e32 v64, v115, v64
	v_add_f32_e32 v64, v116, v64
	v_add_f32_e32 v64, v117, v64
	v_add_f32_e32 v64, v118, v64
	v_add_f32_e32 v64, v119, v64
	v_add_f32_e32 v64, v120, v64
	v_add_f32_e32 v64, v121, v64
	v_add_f32_e32 v64, v122, v64
	v_add_f32_e32 v64, v123, v64
	v_add_f32_e32 v64, v124, v64
	v_add_f32_e32 v64, v125, v64
	v_add_f32_e32 v64, v126, v64
	v_add_f32_e32 v64, v127, v64
	v_add_f32_e32 v64, v64, v96
	v_add_f32_e32 v64, v97, v64
	v_add_f32_e32 v64, v98, v64
	v_add_f32_e32 v64, v99, v64
	v_add_f32_e32 v64, v100, v64
	v_add_f32_e32 v64, v101, v64
	v_add_f32_e32 v64, v102, v64
	v_add_f32_e32 v64, v103, v64
	v_add_f32_e32 v64, v104, v64
	v_add_f32_e32 v64, v105, v64
	v_add_f32_e32 v64, v106, v64
	v_add_f32_e32 v64, v107, v64
	v_add_f32_e32 v64, v108, v64
	v_add_f32_e32 v64, v109, v64
	v_add_f32_e32 v64, v110, v64
	v_add_f32_e32 v89, v111, v64
	v_mov_b32_e32 v73, v89
	v_cvt_pk_bf16_f32 v64, v112, v113
	v_cvt_pk_bf16_f32 v65, v114, v115
	v_cvt_pk_bf16_f32 v66, v116, v117
	v_cvt_pk_bf16_f32 v67, v118, v119
	v_cvt_pk_bf16_f32 v68, v120, v121
	v_cvt_pk_bf16_f32 v69, v122, v123
	v_cvt_pk_bf16_f32 v70, v124, v125
	v_cvt_pk_bf16_f32 v71, v126, v127
	v_cvt_pk_bf16_f32 v74, v96, v97
	v_cvt_pk_bf16_f32 v75, v98, v99
	v_cvt_pk_bf16_f32 v76, v100, v101
	v_cvt_pk_bf16_f32 v77, v102, v103
	s_nop 1
	v_permlane32_swap_b32_e32 v89, v73
	v_permlane32_swap_b32_e32 v68, v70
	v_permlane32_swap_b32_e32 v74, v76
	v_permlane32_swap_b32_e32 v75, v77
	v_cvt_pk_bf16_f32 v78, v104, v105
	v_cvt_pk_bf16_f32 v79, v106, v107
	v_cvt_pk_bf16_f32 v80, v108, v109
	v_cvt_pk_bf16_f32 v81, v110, v111
	v_permlane32_swap_b32_e32 v64, v66
	v_permlane32_swap_b32_e32 v65, v67
	v_permlane32_swap_b32_e32 v69, v71
	v_permlane32_swap_b32_e32 v78, v80
	v_permlane32_swap_b32_e32 v79, v81
	s_cmp_lg_u32 0, -1
	s_cselect_b32 s0, 0, 0
	s_addk_i32 s0, 0x4000
	v_add_u32_e32 v86, s0, v176
	v_add_u32_e32 v86, s100, v86
	ds_read_b64_tr_b16 v[82:83], v86 offset:0
	ds_read_b64_tr_b16 v[84:85], v86 offset:0x800
	ds_read_b64_tr_b16 v[90:91], v86 offset:0x1000
	ds_read_b64_tr_b16 v[92:93], v86 offset:0x1800
	ds_read_b64_tr_b16 v[94:95], v86 offset:0x2000
	ds_read_b64_tr_b16 v[96:97], v86 offset:0x2800
	ds_read_b64_tr_b16 v[98:99], v86 offset:0x3000
	ds_read_b64_tr_b16 v[100:101], v86 offset:0x3800
	s_waitcnt lgkmcnt(0)
	s_nop 0
	v_mfma_f32_32x32x16_bf16 v[48:63], v[64:67], v[82:85], v[48:63]
	ds_read_b64_tr_b16 v[82:83], v86 offset:0x200
	ds_read_b64_tr_b16 v[84:85], v86 offset:0xa00
	v_mfma_f32_32x32x16_bf16 v[48:63], v[68:71], v[90:93], v[48:63]
	ds_read_b64_tr_b16 v[90:91], v86 offset:0x1200
	ds_read_b64_tr_b16 v[92:93], v86 offset:0x1a00
	v_mfma_f32_32x32x16_bf16 v[48:63], v[74:77], v[94:97], v[48:63]
	ds_read_b64_tr_b16 v[94:95], v86 offset:0x2200
	ds_read_b64_tr_b16 v[96:97], v86 offset:0x2a00
	v_mfma_f32_32x32x16_bf16 v[48:63], v[78:81], v[98:101], v[48:63]
	ds_read_b64_tr_b16 v[98:99], v86 offset:0x3200
	ds_read_b64_tr_b16 v[100:101], v86 offset:0x3a00
	s_waitcnt lgkmcnt(0)
	v_mfma_f32_32x32x16_bf16 v[32:47], v[64:67], v[82:85], v[32:47]
	ds_read_b64_tr_b16 v[82:83], v86 offset:0x400
	ds_read_b64_tr_b16 v[84:85], v86 offset:0xc00
	v_mfma_f32_32x32x16_bf16 v[32:47], v[68:71], v[90:93], v[32:47]
	ds_read_b64_tr_b16 v[90:91], v86 offset:0x1400
	ds_read_b64_tr_b16 v[92:93], v86 offset:0x1c00
	v_mfma_f32_32x32x16_bf16 v[32:47], v[74:77], v[94:97], v[32:47]
	ds_read_b64_tr_b16 v[94:95], v86 offset:0x2400
	ds_read_b64_tr_b16 v[96:97], v86 offset:0x2c00
	v_mfma_f32_32x32x16_bf16 v[32:47], v[78:81], v[98:101], v[32:47]
	ds_read_b64_tr_b16 v[98:99], v86 offset:0x3400
	ds_read_b64_tr_b16 v[100:101], v86 offset:0x3c00
	s_waitcnt lgkmcnt(0)
	v_mfma_f32_32x32x16_bf16 v[16:31], v[64:67], v[82:85], v[16:31]
	ds_read_b64_tr_b16 v[82:83], v86 offset:0x600
	ds_read_b64_tr_b16 v[84:85], v86 offset:0xe00
	v_mfma_f32_32x32x16_bf16 v[16:31], v[68:71], v[90:93], v[16:31]
	ds_read_b64_tr_b16 v[90:91], v86 offset:0x1600
	ds_read_b64_tr_b16 v[92:93], v86 offset:0x1e00
	v_mfma_f32_32x32x16_bf16 v[16:31], v[74:77], v[94:97], v[16:31]
	ds_read_b64_tr_b16 v[94:95], v86 offset:0x2600
	ds_read_b64_tr_b16 v[96:97], v86 offset:0x2e00
	v_mfma_f32_32x32x16_bf16 v[16:31], v[78:81], v[98:101], v[16:31]
	ds_read_b64_tr_b16 v[98:99], v86 offset:0x3600
	ds_read_b64_tr_b16 v[100:101], v86 offset:0x3e00
	s_waitcnt lgkmcnt(0)
; __device__ __forceinline__ int crow(int r, int hi) { return (r & 3) + 8 * (r >> 2) + 4 * hi; }
; __device__ __forceinline__ void attn_unit(const bf16* __restrict__ P, bf16* __restrict__ MIXIN, const float* __restrict__ gn, int seq0, int h, int q0, int nt, float kmax0, float kmax1, float slope, float lam, char* lds) {
;     ...
;   int tide_ = threadIdx.x; asm volatile("" : "+v"(tide_)); const int lanee = tide_ & 63, r32e = lanee & 31, hie = lanee >> 5, wide = tide_ >> 6, wqe = wide & 3, mpe = wide >> 2;
;   if (hie == 0) li_l[r32e] = l_reg; asm volatile("s_waitcnt lgkmcnt(0)" ::: "memory");
;   float rli[16];
; #pragma unroll
;   for (int r = 0; r < 16; ++r) rli[r] = __builtin_amdgcn_rcpf(li_l[crow(r, hie)]);
;   asm volatile("s_waitcnt vmcnt(0)" ::: "memory");
;   __syncthreads();
;   float* X = (float*)lds;
;   if (mpe == 1) {
	v_mfma_f32_32x32x16_bf16 v[0:15], v[64:67], v[82:85], v[0:15]
	v_mfma_f32_32x32x16_bf16 v[0:15], v[68:71], v[90:93], v[0:15]
	v_mfma_f32_32x32x16_bf16 v[0:15], v[74:77], v[94:97], v[0:15]
	v_mov_b32_e32 v77, v210
	s_nop 0
	v_and_b32_e32 v68, 63, v77
	v_and_b32_e32 v76, 31, v77
	v_cmp_gt_u32_e32 vcc, 32, v68
	v_mfma_f32_32x32x16_bf16 v[0:15], v[78:81], v[98:101], v[0:15]
	s_and_saveexec_b64 s[0:1], vcc
	v_pk_add_f32 v[64:65], v[88:89], v[72:73]
	v_lshl_add_u32 v66, v76, 2, v144
	v_add_f32_e32 v64, v231, v64
	v_add_f32_e32 v64, v64, v65
	ds_write_b32 v66, v64
	s_or_b64 exec, exec, s[0:1]
	v_lshrrev_b32_e32 v78, 5, v68
	s_waitcnt lgkmcnt(0)
	v_lshl_add_u32 v69, v78, 4, v144
	ds_read_b128 v[64:67], v69
	ds_read_b128 v[70:73], v69 offset:32
	v_lshlrev_b32_e32 v90, 8, v77
	s_waitcnt lgkmcnt(1)
	v_rcp_f32_e32 v94, v64
	v_rcp_f32_e32 v96, v65
	v_rcp_f32_e32 v92, v66
	v_rcp_f32_e32 v93, v67
	s_waitcnt lgkmcnt(0)
	v_rcp_f32_e32 v89, v70
	ds_read_b128 v[64:67], v69 offset:64
	v_rcp_f32_e32 v91, v71
	v_rcp_f32_e32 v80, v72
	v_rcp_f32_e32 v81, v73
	ds_read_b128 v[70:73], v69 offset:96
	s_waitcnt lgkmcnt(1)
	v_rcp_f32_e32 v87, v64
	v_rcp_f32_e32 v88, v65
	v_rcp_f32_e32 v85, v66
	v_rcp_f32_e32 v86, v67
	s_waitcnt lgkmcnt(0)
	v_rcp_f32_e32 v83, v70
	v_rcp_f32_e32 v84, v71
	v_rcp_f32_e32 v82, v72
	v_rcp_f32_e32 v79, v73
	s_waitcnt vmcnt(0)
	v_and_b32_e32 v64, 0xffffff00, v77
	v_cmp_eq_u32_e32 vcc, s28, v64
	v_and_b32_e32 v69, 0xc000, v90
	s_barrier
	s_and_saveexec_b64 s[0:1], vcc
	s_cbranch_execz .LBB0_344
; __device__ __forceinline__ void attn_unit(const bf16* __restrict__ P, bf16* __restrict__ MIXIN, const float* __restrict__ gn, int seq0, int h, int q0, int nt, float kmax0, float kmax1, float slope, float lam, char* lds) {
;     ...
;   if (mpe == 1) {
; #pragma unroll
;     for (int d0 = 0; d0 < 4; ++d0)
; #pragma unroll
;       for (int r = 0; r < 16; ++r) X[(wqe * 64 + d0 * 16 + r) * 64 + lanee] = o[d0][r] * rli[r] * lam;
;   }
	v_lshlrev_b32_e32 v64, 2, v68
	v_mul_f32_e32 v65, v48, v94
	v_mul_f32_e32 v66, v49, v96
	v_mul_f32_e32 v65, v183, v65
	v_add3_u32 v64, 0, v64, v69
	v_mul_f32_e32 v66, v183, v66
	ds_write2st64_b32 v64, v65, v66 offset1:1
	v_mul_f32_e32 v65, v50, v92
	v_mul_f32_e32 v66, v51, v93
	v_mul_f32_e32 v65, v183, v65
	v_mul_f32_e32 v66, v183, v66
	ds_write2st64_b32 v64, v65, v66 offset0:2 offset1:3
	v_mul_f32_e32 v65, v52, v89
	v_mul_f32_e32 v66, v53, v91
	v_mul_f32_e32 v65, v183, v65
	v_mul_f32_e32 v66, v183, v66
	ds_write2st64_b32 v64, v65, v66 offset0:4 offset1:5
	v_mul_f32_e32 v65, v54, v80
	v_mul_f32_e32 v66, v55, v81
	v_mul_f32_e32 v65, v183, v65
	v_mul_f32_e32 v66, v183, v66
	ds_write2st64_b32 v64, v65, v66 offset0:6 offset1:7
	v_mul_f32_e32 v65, v56, v87
	v_mul_f32_e32 v66, v57, v88
	v_mul_f32_e32 v65, v183, v65
	v_mul_f32_e32 v66, v183, v66
	ds_write2st64_b32 v64, v65, v66 offset0:8 offset1:9
	v_mul_f32_e32 v65, v58, v85
	v_mul_f32_e32 v66, v59, v86
	v_mul_f32_e32 v65, v183, v65
	v_mul_f32_e32 v66, v183, v66
	ds_write2st64_b32 v64, v65, v66 offset0:10 offset1:11
	v_mul_f32_e32 v65, v60, v83
	v_mul_f32_e32 v66, v61, v84
	v_mul_f32_e32 v65, v183, v65
	v_mul_f32_e32 v66, v183, v66
	ds_write2st64_b32 v64, v65, v66 offset0:12 offset1:13
	v_mul_f32_e32 v65, v62, v82
	v_mul_f32_e32 v66, v63, v79
	v_mul_f32_e32 v65, v183, v65
	v_mul_f32_e32 v66, v183, v66
	ds_write2st64_b32 v64, v65, v66 offset0:14 offset1:15
	v_mul_f32_e32 v65, v32, v94
	v_mul_f32_e32 v66, v33, v96
	v_mul_f32_e32 v65, v183, v65
	v_mul_f32_e32 v66, v183, v66
	ds_write2st64_b32 v64, v65, v66 offset0:16 offset1:17
	v_mul_f32_e32 v65, v34, v92
	v_mul_f32_e32 v66, v35, v93
	v_mul_f32_e32 v65, v183, v65
	v_mul_f32_e32 v66, v183, v66
	ds_write2st64_b32 v64, v65, v66 offset0:18 offset1:19
	v_mul_f32_e32 v65, v36, v89
	v_mul_f32_e32 v66, v37, v91
	v_mul_f32_e32 v65, v183, v65
	v_mul_f32_e32 v66, v183, v66
	ds_write2st64_b32 v64, v65, v66 offset0:20 offset1:21
	v_mul_f32_e32 v65, v38, v80
	v_mul_f32_e32 v66, v39, v81
	v_mul_f32_e32 v65, v183, v65
	v_mul_f32_e32 v66, v183, v66
	ds_write2st64_b32 v64, v65, v66 offset0:22 offset1:23
	v_mul_f32_e32 v65, v40, v87
	v_mul_f32_e32 v66, v41, v88
	v_mul_f32_e32 v65, v183, v65
	v_mul_f32_e32 v66, v183, v66
	ds_write2st64_b32 v64, v65, v66 offset0:24 offset1:25
	v_mul_f32_e32 v65, v42, v85
	v_mul_f32_e32 v66, v43, v86
	v_mul_f32_e32 v65, v183, v65
	v_mul_f32_e32 v66, v183, v66
	ds_write2st64_b32 v64, v65, v66 offset0:26 offset1:27
	v_mul_f32_e32 v65, v44, v83
	v_mul_f32_e32 v66, v45, v84
	v_mul_f32_e32 v65, v183, v65
	v_mul_f32_e32 v66, v183, v66
	ds_write2st64_b32 v64, v65, v66 offset0:28 offset1:29
	v_mul_f32_e32 v65, v46, v82
	v_mul_f32_e32 v66, v47, v79
	v_mul_f32_e32 v65, v183, v65
	v_mul_f32_e32 v66, v183, v66
	ds_write2st64_b32 v64, v65, v66 offset0:30 offset1:31
	v_mul_f32_e32 v65, v16, v94
	v_mul_f32_e32 v66, v17, v96
	v_mul_f32_e32 v65, v183, v65
	v_mul_f32_e32 v66, v183, v66
	ds_write2st64_b32 v64, v65, v66 offset0:32 offset1:33
	v_mul_f32_e32 v65, v18, v92
	v_mul_f32_e32 v66, v19, v93
	v_mul_f32_e32 v65, v183, v65
	v_mul_f32_e32 v66, v183, v66
	ds_write2st64_b32 v64, v65, v66 offset0:34 offset1:35
	v_mul_f32_e32 v65, v20, v89
	v_mul_f32_e32 v66, v21, v91
	v_mul_f32_e32 v65, v183, v65
	v_mul_f32_e32 v66, v183, v66
	ds_write2st64_b32 v64, v65, v66 offset0:36 offset1:37
	v_mul_f32_e32 v65, v22, v80
	v_mul_f32_e32 v66, v23, v81
	v_mul_f32_e32 v65, v183, v65
	v_mul_f32_e32 v66, v183, v66
	ds_write2st64_b32 v64, v65, v66 offset0:38 offset1:39
	v_mul_f32_e32 v65, v24, v87
	v_mul_f32_e32 v66, v25, v88
	v_mul_f32_e32 v65, v183, v65
	v_mul_f32_e32 v66, v183, v66
	ds_write2st64_b32 v64, v65, v66 offset0:40 offset1:41
	v_mul_f32_e32 v65, v26, v85
	v_mul_f32_e32 v66, v27, v86
	v_mul_f32_e32 v65, v183, v65
	v_mul_f32_e32 v66, v183, v66
	ds_write2st64_b32 v64, v65, v66 offset0:42 offset1:43
	v_mul_f32_e32 v65, v28, v83
	v_mul_f32_e32 v66, v29, v84
	v_mul_f32_e32 v65, v183, v65
	v_mul_f32_e32 v66, v183, v66
	ds_write2st64_b32 v64, v65, v66 offset0:44 offset1:45
	v_mul_f32_e32 v65, v30, v82
	v_mul_f32_e32 v66, v31, v79
	v_mul_f32_e32 v65, v183, v65
	v_mul_f32_e32 v66, v183, v66
	ds_write2st64_b32 v64, v65, v66 offset0:46 offset1:47
	v_mul_f32_e32 v65, v0, v94
	v_mul_f32_e32 v66, v1, v96
	v_mul_f32_e32 v65, v183, v65
	v_mul_f32_e32 v66, v183, v66
	ds_write2st64_b32 v64, v65, v66 offset0:48 offset1:49
	v_mul_f32_e32 v65, v2, v92
	v_mul_f32_e32 v66, v3, v93
	v_mul_f32_e32 v65, v183, v65
	v_mul_f32_e32 v66, v183, v66
	ds_write2st64_b32 v64, v65, v66 offset0:50 offset1:51
	v_mul_f32_e32 v65, v4, v89
	v_mul_f32_e32 v66, v5, v91
	v_mul_f32_e32 v65, v183, v65
	v_mul_f32_e32 v66, v183, v66
	ds_write2st64_b32 v64, v65, v66 offset0:52 offset1:53
	v_mul_f32_e32 v65, v6, v80
	v_mul_f32_e32 v66, v7, v81
	v_mul_f32_e32 v65, v183, v65
	v_mul_f32_e32 v66, v183, v66
	ds_write2st64_b32 v64, v65, v66 offset0:54 offset1:55
	v_mul_f32_e32 v65, v8, v87
	v_mul_f32_e32 v66, v9, v88
	v_mul_f32_e32 v65, v183, v65
	v_mul_f32_e32 v66, v183, v66
	ds_write2st64_b32 v64, v65, v66 offset0:56 offset1:57
	v_mul_f32_e32 v65, v10, v85
	v_mul_f32_e32 v66, v11, v86
	v_mul_f32_e32 v65, v183, v65
	v_mul_f32_e32 v66, v183, v66
	ds_write2st64_b32 v64, v65, v66 offset0:58 offset1:59
	v_mul_f32_e32 v65, v12, v83
	v_mul_f32_e32 v66, v13, v84
	v_mul_f32_e32 v65, v183, v65
	v_mul_f32_e32 v66, v183, v66
	ds_write2st64_b32 v64, v65, v66 offset0:60 offset1:61
	v_mul_f32_e32 v65, v14, v82
	v_mul_f32_e32 v66, v15, v79
	v_mul_f32_e32 v65, v183, v65
	v_mul_f32_e32 v66, v183, v66
	ds_write2st64_b32 v64, v65, v66 offset0:62 offset1:63
